# e10 + RG-LRU scan loops: EXEC-masked if/else for (1-a^2) replaced by branch-free compare/select
# baseline (speedup 1.0000x reference)
; __device__ __forceinline__ float bflo(unsigned w) { return __uint_as_float(w << 16); }
; __device__ __forceinline__ float bfhi(unsigned w) { return __uint_as_float(w & 0xffff0000u); }
; __device__ __forceinline__ float fast_exp2(float x) { return __builtin_amdgcn_exp2f(x); }
; __device__ __forceinline__ void lru_coef(const u32x4 xw, const u32x4 aw, const u32x4 uw, const float (&sp)[8], const float (&bxv)[8], const float (&bav)[8], float (&l8)[8], float (&b8)[8]) {
;     const float gx[8] = {bflo(xw.x), bfhi(xw.x), bflo(xw.y), bfhi(xw.y), bflo(xw.z), bfhi(xw.z), bflo(xw.w), bfhi(xw.w)};
;     const float ga[8] = {bflo(aw.x), bfhi(aw.x), bflo(aw.y), bfhi(aw.y), bflo(aw.z), bfhi(aw.z), bflo(aw.w), bfhi(aw.w)};
;     const float uu[8] = {bflo(uw.x), bfhi(uw.x), bflo(uw.y), bfhi(uw.y), bflo(uw.z), bfhi(uw.z), bflo(uw.w), bfhi(uw.w)};
; #pragma unroll
;     for (int j = 0; j < 8; ++j) {
;         const float sx = __builtin_amdgcn_rcpf(1.0f + __builtin_amdgcn_exp2f(-(gx[j] + bxv[j]) * LOG2E));
;         const float sa = __builtin_amdgcn_rcpf(1.0f + __builtin_amdgcn_exp2f(-(ga[j] + bav[j]) * LOG2E));
;         const float la = sa * sp[j];
;         const float x2 = 2.0f * la;
;         const float om = (x2 > -0.02f) ? -x2 * (1.0f + x2 * (0.5f + x2 * 0.16666667f)) : 1.0f - __builtin_amdgcn_exp2f(x2 * LOG2E);
;         l8[j] = la * LOG2E; b8[j] = __builtin_amdgcn_sqrtf(fmaxf(om, 0.f)) * sx * uu[j];
;     }
; __global__ void __launch_bounds__(NT_, 2) fwd_mega(Args args) {
;     ...
;                     float l8[8], b8[8]; lru_coef(lw, bw, uw, sp, bxv, bav, l8, b8);
; #pragma unroll
;                     for (int j = 0; j < 8; ++j) { sl[j] += l8[j]; h[j] = fast_exp2(l8[j]) * h[j] + b8[j]; }
.LBB0_738:
	v_lshlrev_b32_e32 v71, 16, v57
	v_add_f32_e32 v71, v8, v71
	v_mul_f32_e32 v71, 0xbfb8aa3b, v71
	v_exp_f32_e32 v71, v71
	v_max_f32_e32 v60, v60, v60
	v_max_f32_e32 v60, 0, v60
	v_sqrt_f32_e32 v60, v60
	v_add_f32_e32 v71, 1.0, v71
	v_rcp_f32_e32 v71, v71
	s_waitcnt vmcnt(0) lgkmcnt(0)
	v_lshlrev_b32_e32 v96, 16, v53
	v_and_b32_e32 v97, 0xffff0000, v52
	v_lshlrev_b32_e32 v52, 16, v52
	v_mul_f32_e32 v60, v71, v60
	v_and_b32_e32 v71, 0xffff0000, v56
	v_add_f32_e32 v71, v7, v71
	v_mul_f32_e32 v71, 0xbfb8aa3b, v71
	v_lshlrev_b32_e32 v56, 16, v56
	v_exp_f32_e32 v71, v71
	v_add_f32_e32 v56, v6, v56
	v_mul_f32_e32 v56, 0xbfb8aa3b, v56
	v_exp_f32_e32 v56, v56
	v_add_f32_e32 v71, 1.0, v71
	v_mul_f32_e32 v60, v60, v96
	v_rcp_f32_e32 v96, v71
	v_mul_f32_e32 v71, 0x3fb8aa3b, v69
	v_max_f32_e32 v69, v70, v70
	v_mul_f32_e32 v70, 0x3fb8aa3b, v68
	v_max_f32_e32 v68, v95, v95
	v_add_f32_e32 v56, 1.0, v56
	v_max_f32_e32 v68, 0, v68
	v_rcp_f32_e32 v56, v56
	v_sqrt_f32_e32 v68, v68
	v_max_f32_e32 v75, v75, v75
	v_max_f32_e32 v75, 0, v75
	v_sqrt_f32_e32 v75, v75
	v_mul_f32_e32 v56, v56, v68
	v_mul_f32_e32 v68, v56, v52
	v_and_b32_e32 v52, 0xffff0000, v55
	v_add_f32_e32 v52, v5, v52
	v_mul_f32_e32 v52, 0xbfb8aa3b, v52
	v_exp_f32_e32 v52, v52
	v_and_b32_e32 v56, 0xffff0000, v51
	v_lshlrev_b32_e32 v51, 16, v51
	v_max_f32_e32 v78, v78, v78
	v_add_f32_e32 v52, 1.0, v52
	v_rcp_f32_e32 v52, v52
	v_max_f32_e32 v78, 0, v78
	v_sqrt_f32_e32 v78, v78
	v_max_f32_e32 v83, v83, v83
	v_mul_f32_e32 v52, v52, v75
	v_mul_f32_e32 v75, v52, v56
	v_lshlrev_b32_e32 v52, 16, v55
	v_add_f32_e32 v52, v4, v52
	v_mul_f32_e32 v52, 0xbfb8aa3b, v52
	v_exp_f32_e32 v52, v52
	v_max_f32_e32 v55, v74, v74
	v_max_f32_e32 v55, 0, v55
	v_sqrt_f32_e32 v55, v55
	v_add_f32_e32 v52, 1.0, v52
	v_rcp_f32_e32 v52, v52
	v_max_f32_e32 v56, v94, v94
	v_max_f32_e32 v56, 0, v56
	v_sqrt_f32_e32 v56, v56
	v_mul_f32_e32 v52, v52, v55
	v_mul_f32_e32 v74, v52, v51
	v_and_b32_e32 v51, 0xffff0000, v54
	v_add_f32_e32 v51, v3, v51
	v_mul_f32_e32 v51, 0xbfb8aa3b, v51
	v_exp_f32_e32 v51, v51
	v_and_b32_e32 v52, 0xffff0000, v50
	v_lshlrev_b32_e32 v50, 16, v50
	v_max_f32_e32 v83, 0, v83
	v_add_f32_e32 v51, 1.0, v51
	v_rcp_f32_e32 v51, v51
	v_sqrt_f32_e32 v83, v83
	v_mul_f32_e32 v55, 0x3fb8aa3b, v93
	v_mul_f32_e32 v81, 0x3fb8aa3b, v81
	v_mul_f32_e32 v51, v51, v56
	v_mul_f32_e32 v51, v51, v52
	v_lshlrev_b32_e32 v52, 16, v54
	v_add_f32_e32 v52, v2, v52
	v_mul_f32_e32 v52, 0xbfb8aa3b, v52
	v_exp_f32_e32 v52, v52
	v_max_f32_e32 v56, v92, v92
	v_max_f32_e32 v56, 0, v56
	v_sqrt_f32_e32 v56, v56
	v_add_f32_e32 v52, 1.0, v52
	v_rcp_f32_e32 v52, v52
	v_mul_f32_e32 v54, 0x3fb8aa3b, v91
	v_mul_f32_e32 v91, 0x3fb8aa3b, v89
	v_mul_f32_e32 v80, 0x3fb8aa3b, v80
	v_mul_f32_e32 v52, v52, v56
	v_mul_f32_e32 v50, v52, v50
	v_lshlrev_b32_e32 v52, 16, v49
	v_add_f32_e32 v52, v8, v52
	v_mul_f32_e32 v52, 0xbfb8aa3b, v52
	v_exp_f32_e32 v52, v52
	v_lshlrev_b32_e32 v56, 16, v45
	v_mul_f32_e32 v76, 0x3fb8aa3b, v76
	v_mul_f32_e32 v73, 0x3fb8aa3b, v73
	v_add_f32_e32 v52, 1.0, v52
	v_rcp_f32_e32 v52, v52
	v_mul_f32_e32 v72, 0x3fb8aa3b, v72
	v_max_f32_e32 v69, 0, v69
	v_sqrt_f32_e32 v69, v69
	v_mul_f32_e32 v52, v52, v78
	v_mul_f32_e32 v78, v52, v56
	v_and_b32_e32 v52, 0xffff0000, v48
	v_add_f32_e32 v52, v7, v52
	v_mul_f32_e32 v52, 0xbfb8aa3b, v52
	v_exp_f32_e32 v52, v52
	v_lshlrev_b32_e32 v48, 16, v48
	v_add_f32_e32 v48, v6, v48
	v_mul_f32_e32 v48, 0xbfb8aa3b, v48
	v_add_f32_e32 v52, 1.0, v52
	v_rcp_f32_e32 v52, v52
	v_exp_f32_e32 v48, v48
	v_and_b32_e32 v56, 0xffff0000, v44
	v_lshlrev_b32_e32 v44, 16, v44
	v_mul_f32_e32 v52, v52, v83
	v_mul_f32_e32 v83, v52, v56
	v_max_f32_e32 v52, v82, v82
	v_add_f32_e32 v48, 1.0, v48
	v_max_f32_e32 v52, 0, v52
	v_rcp_f32_e32 v48, v48
	v_sqrt_f32_e32 v52, v52
	v_mul_f32_e32 v69, v96, v69
	v_mul_f32_e32 v58, 0x3fb8aa3b, v58
	v_mul_f32_e32 v69, v69, v97
	v_mul_f32_e32 v48, v48, v52
	v_mul_f32_e32 v82, v48, v44
	v_and_b32_e32 v44, 0xffff0000, v47
	v_add_f32_e32 v44, v5, v44
	v_mul_f32_e32 v44, 0xbfb8aa3b, v44
	v_exp_f32_e32 v44, v44
	v_max_f32_e32 v52, v90, v90
	v_max_f32_e32 v52, 0, v52
	v_sqrt_f32_e32 v52, v52
	v_add_f32_e32 v44, 1.0, v44
	v_rcp_f32_e32 v44, v44
	v_and_b32_e32 v48, 0xffff0000, v43
	v_lshlrev_b32_e32 v43, 16, v43
	v_mul_f32_e32 v90, 0x3fb8aa3b, v85
	v_mul_f32_e32 v44, v44, v52
	v_mul_f32_e32 v93, v44, v48
	v_lshlrev_b32_e32 v44, 16, v47
	v_add_f32_e32 v44, v4, v44
	v_mul_f32_e32 v44, 0xbfb8aa3b, v44
	v_exp_f32_e32 v44, v44
	v_max_f32_e32 v47, v86, v86
	v_max_f32_e32 v47, 0, v47
	v_sqrt_f32_e32 v47, v47
	v_add_f32_e32 v44, 1.0, v44
	v_rcp_f32_e32 v44, v44
	v_max_f32_e32 v48, v79, v79
	v_max_f32_e32 v48, 0, v48
	v_sqrt_f32_e32 v48, v48
	v_mul_f32_e32 v44, v44, v47
	v_mul_f32_e32 v92, v44, v43
	v_and_b32_e32 v43, 0xffff0000, v46
	v_add_f32_e32 v43, v3, v43
	v_mul_f32_e32 v43, 0xbfb8aa3b, v43
	v_exp_f32_e32 v43, v43
	v_and_b32_e32 v47, 0xffff0000, v42
	v_mul_f32_e32 v59, 0x3fb8aa3b, v59
	s_add_u32 s10, s10, 0x1000
	v_add_f32_e32 v43, 1.0, v43
	v_rcp_f32_e32 v44, v43
	v_mul_f32_e32 v43, 0x3fb8aa3b, v77
	v_mul_f32_e32 v77, 0x3fb8aa3b, v87
	v_pk_add_f32 v[32:33], v[90:91], v[32:33]
	v_mul_f32_e32 v44, v44, v48
	v_mul_f32_e32 v47, v44, v47
	v_lshlrev_b32_e32 v44, 16, v46
	v_lshlrev_b32_e32 v46, 16, v42
	v_add_f32_e32 v42, v2, v44
	v_mul_f32_e32 v42, 0xbfb8aa3b, v42
	v_exp_f32_e32 v42, v42
	v_pk_add_f32 v[34:35], v[80:81], v[34:35]
	v_pk_add_f32 v[36:37], v[76:77], v[36:37]
	s_addc_u32 s11, s11, 0
	v_add_f32_e32 v42, 1.0, v42
	v_rcp_f32_e32 v44, v42
	v_mul_f32_e32 v42, 0x3fb8aa3b, v0
	v_max_f32_e32 v0, v65, v65
	v_max_f32_e32 v0, 0, v0
	v_sqrt_f32_e32 v0, v0
	v_pk_add_f32 v[30:31], v[42:43], v[30:31]
; __device__ __forceinline__ float bflo(unsigned w) { return __uint_as_float(w << 16); }
; __device__ __forceinline__ float bfhi(unsigned w) { return __uint_as_float(w & 0xffff0000u); }
; __device__ __forceinline__ float fast_exp2(float x) { return __builtin_amdgcn_exp2f(x); }
; __device__ __forceinline__ void lru_coef(const u32x4 xw, const u32x4 aw, const u32x4 uw, const float (&sp)[8], const float (&bxv)[8], const float (&bav)[8], float (&l8)[8], float (&b8)[8]) {
;     const float gx[8] = {bflo(xw.x), bfhi(xw.x), bflo(xw.y), bfhi(xw.y), bflo(xw.z), bfhi(xw.z), bflo(xw.w), bfhi(xw.w)};
;     const float ga[8] = {bflo(aw.x), bfhi(aw.x), bflo(aw.y), bfhi(aw.y), bflo(aw.z), bfhi(aw.z), bflo(aw.w), bfhi(aw.w)};
;     const float uu[8] = {bflo(uw.x), bfhi(uw.x), bflo(uw.y), bfhi(uw.y), bflo(uw.z), bfhi(uw.z), bflo(uw.w), bfhi(uw.w)};
; #pragma unroll
;     for (int j = 0; j < 8; ++j) {
;         const float sx = __builtin_amdgcn_rcpf(1.0f + __builtin_amdgcn_exp2f(-(gx[j] + bxv[j]) * LOG2E));
;         const float sa = __builtin_amdgcn_rcpf(1.0f + __builtin_amdgcn_exp2f(-(ga[j] + bav[j]) * LOG2E));
;         const float la = sa * sp[j];
;         const float x2 = 2.0f * la;
;         const float om = (x2 > -0.02f) ? -x2 * (1.0f + x2 * (0.5f + x2 * 0.16666667f)) : 1.0f - __builtin_amdgcn_exp2f(x2 * LOG2E);
;         l8[j] = la * LOG2E; b8[j] = __builtin_amdgcn_sqrtf(fmaxf(om, 0.f)) * sx * uu[j];
;     }
; __global__ void __launch_bounds__(NT_, 2) fwd_mega(Args args) {
;     ...
;                     const u32x4 lw = *(const u32x4*)(LAb + (t0 + st) * 1024 + ch), bw = *(const u32x4*)(BVb + (t0 + st) * 1024 + ch), uw = *(const u32x4*)(UCb + (t0 + st) * 1024 + ch);
;                     float l8[8], b8[8]; lru_coef(lw, bw, uw, sp, bxv, bav, l8, b8);
; #pragma unroll
;                     for (int j = 0; j < 8; ++j) { sl[j] += l8[j]; h[j] = fast_exp2(l8[j]) * h[j] + b8[j]; }
	v_pk_add_f32 v[32:33], v[72:73], v[32:33]
	v_pk_add_f32 v[30:31], v[54:55], v[30:31]
	v_mul_f32_e32 v0, v44, v0
	v_mul_f32_e32 v46, v0, v46
	v_and_b32_e32 v0, 0xffff0000, v49
	v_add_f32_e32 v0, v9, v0
	v_mul_f32_e32 v0, 0xbfb8aa3b, v0
	v_exp_f32_e32 v0, v0
	v_and_b32_e32 v44, 0xffff0000, v45
	v_max_f32_e32 v45, v88, v88
	v_max_f32_e32 v45, 0, v45
	v_add_f32_e32 v0, 1.0, v0
	v_rcp_f32_e32 v0, v0
	v_sqrt_f32_e32 v45, v45
	v_pk_add_f32 v[34:35], v[70:71], v[34:35]
	v_pk_add_f32 v[36:37], v[58:59], v[36:37]
	s_cmp_eq_u32 s10, 0x20000
	v_mul_f32_e32 v0, v0, v45
	v_mul_f32_e32 v79, v0, v44
	v_exp_f32_e32 v44, v42
	v_exp_f32_e32 v45, v43
	v_exp_f32_e32 v42, v90
	v_exp_f32_e32 v43, v91
	v_and_b32_e32 v0, 0xffff0000, v57
	v_add_f32_e32 v0, v9, v0
	v_mul_f32_e32 v0, 0xbfb8aa3b, v0
	v_pk_fma_f32 v[28:29], v[42:43], v[28:29], v[92:93]
	v_exp_f32_e32 v42, v80
	v_exp_f32_e32 v43, v81
	v_exp_f32_e32 v0, v0
	v_pk_fma_f32 v[26:27], v[44:45], v[26:27], v[46:47]
	v_pk_fma_f32 v[38:39], v[42:43], v[38:39], v[82:83]
	v_exp_f32_e32 v42, v76
	v_exp_f32_e32 v43, v77
	v_add_f32_e32 v0, 1.0, v0
	v_rcp_f32_e32 v0, v0
	v_pk_fma_f32 v[40:41], v[42:43], v[40:41], v[78:79]
	v_max_f32_e32 v43, v61, v61
	v_max_f32_e32 v43, 0, v43
	v_sqrt_f32_e32 v43, v43
	v_and_b32_e32 v42, 0xffff0000, v53
	v_mul_f32_e32 v0, v0, v43
	v_mul_f32_e32 v61, v0, v42
	v_exp_f32_e32 v42, v54
	v_exp_f32_e32 v43, v55
	s_nop 0
	v_pk_fma_f32 v[26:27], v[42:43], v[26:27], v[50:51]
	v_exp_f32_e32 v42, v72
	v_exp_f32_e32 v43, v73
	s_nop 0
	v_pk_fma_f32 v[28:29], v[42:43], v[28:29], v[74:75]
	v_exp_f32_e32 v42, v70
	v_exp_f32_e32 v43, v71
	s_nop 0
	v_pk_fma_f32 v[38:39], v[42:43], v[38:39], v[68:69]
	v_exp_f32_e32 v42, v58
	v_exp_f32_e32 v43, v59
	s_nop 0
	v_pk_fma_f32 v[40:41], v[42:43], v[40:41], v[60:61]
	s_cbranch_scc1 .LBB0_736
.LBB0_739:
	v_lshl_add_u64 v[68:69], v[66:67], 0, s[10:11]
	v_add_co_u32_e32 v42, vcc, 0x28000000, v68
	s_nop 1
	v_addc_co_u32_e32 v43, vcc, 0, v69, vcc
	v_add_co_u32_e32 v44, vcc, 0x8000000, v68
	s_nop 1
	v_addc_co_u32_e32 v45, vcc, 0, v69, vcc
	flat_load_dwordx4 v[50:53], v[44:45]
	flat_load_dwordx4 v[46:49], v[42:43]
	v_add_co_u32_e32 v42, vcc, 0x20000000, v68
	s_waitcnt vmcnt(0) lgkmcnt(0)
	v_lshlrev_b32_e32 v0, 16, v50
	v_addc_co_u32_e32 v43, vcc, 0, v69, vcc
	flat_load_dwordx4 v[42:45], v[42:43]
	v_add_f32_e32 v0, v10, v0
	v_mul_f32_e32 v0, 0xbfb8aa3b, v0
	v_exp_f32_e32 v0, v0
	s_nop 0
	v_add_f32_e32 v0, 1.0, v0
	v_rcp_f32_e32 v0, v0
	s_nop 0
	v_mul_f32_e32 v0, v18, v0
	v_add_f32_e32 v54, v0, v0
	v_cmp_nlt_f32_e32 vcc, s88, v54
	v_fma_f32 v150, v54, s72, 0.5
	v_fma_f32 v150, v54, v150, 1.0
	v_mul_f32_e64 v150, v150, -v54
	v_mul_f32_e32 v54, 0x3fb8aa3b, v54
	v_exp_f32_e32 v54, v54
	s_nop 0
	v_sub_f32_e32 v65, 1.0, v54
	v_cndmask_b32_e32 v65, v150, v65, vcc
	v_and_b32_e32 v50, 0xffff0000, v50
	v_add_f32_e32 v50, v11, v50
	v_mul_f32_e32 v50, 0xbfb8aa3b, v50
	v_exp_f32_e32 v50, v50
	s_nop 0
	v_add_f32_e32 v50, 1.0, v50
	v_rcp_f32_e32 v50, v50
	s_nop 0
	v_mul_f32_e32 v77, v19, v50
	v_add_f32_e32 v50, v77, v77
	v_cmp_nlt_f32_e32 vcc, s88, v50
	v_fma_f32 v150, v50, s72, 0.5
	v_fma_f32 v150, v50, v150, 1.0
	v_mul_f32_e64 v150, v150, -v50
	v_mul_f32_e32 v50, 0x3fb8aa3b, v50
	v_exp_f32_e32 v50, v50
	s_nop 0
	v_sub_f32_e32 v79, 1.0, v50
	v_cndmask_b32_e32 v79, v150, v79, vcc
	v_lshlrev_b32_e32 v50, 16, v51
	v_add_f32_e32 v50, v12, v50
	v_mul_f32_e32 v50, 0xbfb8aa3b, v50
	v_exp_f32_e32 v50, v50
	s_nop 0
	v_add_f32_e32 v50, 1.0, v50
	v_rcp_f32_e32 v50, v50
	s_nop 0
	v_mul_f32_e32 v85, v20, v50
	v_add_f32_e32 v50, v85, v85
	v_cmp_nlt_f32_e32 vcc, s88, v50
	v_fma_f32 v150, v50, s72, 0.5
	v_fma_f32 v150, v50, v150, 1.0
	v_mul_f32_e64 v150, v150, -v50
	v_mul_f32_e32 v50, 0x3fb8aa3b, v50
	v_exp_f32_e32 v50, v50
	s_nop 0
	v_sub_f32_e32 v86, 1.0, v50
	v_cndmask_b32_e32 v86, v150, v86, vcc
	v_and_b32_e32 v50, 0xffff0000, v51
	v_add_f32_e32 v50, v13, v50
	v_mul_f32_e32 v50, 0xbfb8aa3b, v50
	v_exp_f32_e32 v50, v50
	s_nop 0
	v_add_f32_e32 v50, 1.0, v50
	v_rcp_f32_e32 v50, v50
	s_nop 0
	v_mul_f32_e32 v89, v21, v50
	v_add_f32_e32 v50, v89, v89
	v_cmp_nlt_f32_e32 vcc, s88, v50
	v_fma_f32 v150, v50, s72, 0.5
	v_fma_f32 v150, v50, v150, 1.0
	v_mul_f32_e64 v150, v150, -v50
	v_mul_f32_e32 v50, 0x3fb8aa3b, v50
	v_exp_f32_e32 v50, v50
	s_nop 0
	v_sub_f32_e32 v90, 1.0, v50
	v_cndmask_b32_e32 v90, v150, v90, vcc
	v_lshlrev_b32_e32 v50, 16, v52
	v_add_f32_e32 v50, v14, v50
	v_mul_f32_e32 v50, 0xbfb8aa3b, v50
	v_exp_f32_e32 v50, v50
	s_nop 0
	v_add_f32_e32 v50, 1.0, v50
	v_rcp_f32_e32 v50, v50
	s_nop 0
	v_mul_f32_e32 v80, v22, v50
	v_add_f32_e32 v50, v80, v80
	v_cmp_nlt_f32_e32 vcc, s88, v50
	v_fma_f32 v150, v50, s72, 0.5
	v_fma_f32 v150, v50, v150, 1.0
	v_mul_f32_e64 v150, v150, -v50
	v_mul_f32_e32 v50, 0x3fb8aa3b, v50
	v_exp_f32_e32 v50, v50
	s_nop 0
	v_sub_f32_e32 v82, 1.0, v50
	v_cndmask_b32_e32 v82, v150, v82, vcc
	v_and_b32_e32 v50, 0xffff0000, v52
	v_add_f32_e32 v50, v15, v50
	v_mul_f32_e32 v50, 0xbfb8aa3b, v50
	v_exp_f32_e32 v50, v50
	s_nop 0
	v_add_f32_e32 v50, 1.0, v50
	v_rcp_f32_e32 v50, v50
	s_nop 0
	v_mul_f32_e32 v81, v23, v50
	v_add_f32_e32 v50, v81, v81
	v_cmp_nlt_f32_e32 vcc, s88, v50
	v_fma_f32 v150, v50, s72, 0.5
	v_fma_f32 v150, v50, v150, 1.0
	v_mul_f32_e64 v150, v150, -v50
	v_mul_f32_e32 v50, 0x3fb8aa3b, v50
	v_exp_f32_e32 v50, v50
	s_nop 0
	v_sub_f32_e32 v83, 1.0, v50
	v_cndmask_b32_e32 v83, v150, v83, vcc
	v_lshlrev_b32_e32 v50, 16, v53
	v_add_f32_e32 v50, v16, v50
	v_mul_f32_e32 v50, 0xbfb8aa3b, v50
	v_exp_f32_e32 v50, v50
	s_nop 0
	v_add_f32_e32 v50, 1.0, v50
	v_rcp_f32_e32 v50, v50
	s_nop 0
	v_mul_f32_e32 v76, v24, v50
	v_add_f32_e32 v50, v76, v76
	v_cmp_nlt_f32_e32 vcc, s88, v50
	v_fma_f32 v150, v50, s72, 0.5
	v_fma_f32 v150, v50, v150, 1.0
	v_mul_f32_e64 v150, v150, -v50
	v_mul_f32_e32 v50, 0x3fb8aa3b, v50
	v_exp_f32_e32 v50, v50
	s_nop 0
	v_sub_f32_e32 v78, 1.0, v50
	v_cndmask_b32_e32 v78, v150, v78, vcc
	v_and_b32_e32 v50, 0xffff0000, v53
	v_add_f32_e32 v50, v17, v50
	v_mul_f32_e32 v50, 0xbfb8aa3b, v50
	v_exp_f32_e32 v50, v50
	s_nop 0
	v_add_f32_e32 v50, 1.0, v50
	v_rcp_f32_e32 v50, v50
	s_nop 0
	v_mul_f32_e32 v87, v25, v50
	v_add_f32_e32 v50, v87, v87
	v_cmp_nlt_f32_e32 vcc, s88, v50
	v_fma_f32 v150, v50, s72, 0.5
	v_fma_f32 v150, v50, v150, 1.0
	v_mul_f32_e64 v150, v150, -v50
	v_mul_f32_e32 v50, 0x3fb8aa3b, v50
	v_exp_f32_e32 v50, v50
	s_nop 0
	v_sub_f32_e32 v88, 1.0, v50
	v_cndmask_b32_e32 v88, v150, v88, vcc
	v_add_co_u32_e32 v50, vcc, 0x28000000, v68
	s_nop 1
	v_addc_co_u32_e32 v51, vcc, 0, v69, vcc
	v_add_co_u32_e32 v52, vcc, 0x8000000, v68
	s_nop 1
	v_addc_co_u32_e32 v53, vcc, 0, v69, vcc
	flat_load_dwordx4 v[58:61], v[52:53] offset:2048
	flat_load_dwordx4 v[54:57], v[50:51] offset:2048
	v_add_co_u32_e32 v50, vcc, 0x20000000, v68
	s_waitcnt vmcnt(0) lgkmcnt(0)
; __device__ __forceinline__ float bflo(unsigned w) { return __uint_as_float(w << 16); }
; __device__ __forceinline__ float bfhi(unsigned w) { return __uint_as_float(w & 0xffff0000u); }
; __device__ __forceinline__ void lru_coef(const u32x4 xw, const u32x4 aw, const u32x4 uw, const float (&sp)[8], const float (&bxv)[8], const float (&bav)[8], float (&l8)[8], float (&b8)[8]) {
;     const float gx[8] = {bflo(xw.x), bfhi(xw.x), bflo(xw.y), bfhi(xw.y), bflo(xw.z), bfhi(xw.z), bflo(xw.w), bfhi(xw.w)};
;     const float ga[8] = {bflo(aw.x), bfhi(aw.x), bflo(aw.y), bfhi(aw.y), bflo(aw.z), bfhi(aw.z), bflo(aw.w), bfhi(aw.w)};
;     const float uu[8] = {bflo(uw.x), bfhi(uw.x), bflo(uw.y), bfhi(uw.y), bflo(uw.z), bfhi(uw.z), bflo(uw.w), bfhi(uw.w)};
; #pragma unroll
;     for (int j = 0; j < 8; ++j) {
;         const float sx = __builtin_amdgcn_rcpf(1.0f + __builtin_amdgcn_exp2f(-(gx[j] + bxv[j]) * LOG2E));
;         const float sa = __builtin_amdgcn_rcpf(1.0f + __builtin_amdgcn_exp2f(-(ga[j] + bav[j]) * LOG2E));
;         const float la = sa * sp[j];
;         const float x2 = 2.0f * la;
;         const float om = (x2 > -0.02f) ? -x2 * (1.0f + x2 * (0.5f + x2 * 0.16666667f)) : 1.0f - __builtin_amdgcn_exp2f(x2 * LOG2E);
;         l8[j] = la * LOG2E; b8[j] = __builtin_amdgcn_sqrtf(fmaxf(om, 0.f)) * sx * uu[j];
;     }
	v_lshlrev_b32_e32 v68, 16, v58
	v_addc_co_u32_e32 v51, vcc, 0, v69, vcc
	flat_load_dwordx4 v[50:53], v[50:51] offset:2048
	v_add_f32_e32 v68, v10, v68
	v_mul_f32_e32 v68, 0xbfb8aa3b, v68
	v_exp_f32_e32 v68, v68
	s_nop 0
	v_add_f32_e32 v68, 1.0, v68
	v_rcp_f32_e32 v68, v68
	s_nop 0
	v_mul_f32_e32 v91, v18, v68
	v_add_f32_e32 v68, v91, v91
	v_cmp_nlt_f32_e32 vcc, s88, v68
	v_fma_f32 v150, v68, s72, 0.5
	v_fma_f32 v150, v68, v150, 1.0
	v_mul_f32_e64 v150, v150, -v68
	v_mul_f32_e32 v68, 0x3fb8aa3b, v68
	v_exp_f32_e32 v68, v68
	s_nop 0
	v_sub_f32_e32 v92, 1.0, v68
	v_cndmask_b32_e32 v92, v150, v92, vcc
	v_and_b32_e32 v58, 0xffff0000, v58
	v_add_f32_e32 v58, v11, v58
	v_mul_f32_e32 v58, 0xbfb8aa3b, v58
	v_exp_f32_e32 v58, v58
	s_nop 0
	v_add_f32_e32 v58, 1.0, v58
	v_rcp_f32_e32 v58, v58
	s_nop 0
	v_mul_f32_e32 v93, v19, v58
	v_add_f32_e32 v58, v93, v93
	v_cmp_nlt_f32_e32 vcc, s88, v58
	v_fma_f32 v150, v58, s72, 0.5
	v_fma_f32 v150, v58, v150, 1.0
	v_mul_f32_e64 v150, v150, -v58
	v_mul_f32_e32 v58, 0x3fb8aa3b, v58
	v_exp_f32_e32 v58, v58
	s_nop 0
	v_sub_f32_e32 v94, 1.0, v58
	v_cndmask_b32_e32 v94, v150, v94, vcc
	v_lshlrev_b32_e32 v58, 16, v59
	v_add_f32_e32 v58, v12, v58
	v_mul_f32_e32 v58, 0xbfb8aa3b, v58
	v_exp_f32_e32 v58, v58
	s_nop 0
	v_add_f32_e32 v58, 1.0, v58
	v_rcp_f32_e32 v58, v58
	s_nop 0
	v_mul_f32_e32 v72, v20, v58
	v_add_f32_e32 v58, v72, v72
	v_cmp_nlt_f32_e32 vcc, s88, v58
	v_fma_f32 v150, v58, s72, 0.5
	v_fma_f32 v150, v58, v150, 1.0
	v_mul_f32_e64 v150, v150, -v58
	v_mul_f32_e32 v58, 0x3fb8aa3b, v58
	v_exp_f32_e32 v58, v58
	s_nop 0
	v_sub_f32_e32 v74, 1.0, v58
	v_cndmask_b32_e32 v74, v150, v74, vcc
	v_and_b32_e32 v58, 0xffff0000, v59
	v_add_f32_e32 v58, v13, v58
	v_mul_f32_e32 v58, 0xbfb8aa3b, v58
	v_exp_f32_e32 v58, v58
	s_nop 0
	v_add_f32_e32 v58, 1.0, v58
	v_rcp_f32_e32 v58, v58
	s_nop 0
	v_mul_f32_e32 v73, v21, v58
	v_add_f32_e32 v58, v73, v73
	v_cmp_nlt_f32_e32 vcc, s88, v58
	v_fma_f32 v150, v58, s72, 0.5
	v_fma_f32 v150, v58, v150, 1.0
	v_mul_f32_e64 v150, v150, -v58
	v_mul_f32_e32 v58, 0x3fb8aa3b, v58
	v_exp_f32_e32 v58, v58
	s_nop 0
	v_sub_f32_e32 v75, 1.0, v58
	v_cndmask_b32_e32 v75, v150, v75, vcc
	v_lshlrev_b32_e32 v58, 16, v60
	v_add_f32_e32 v58, v14, v58
	v_mul_f32_e32 v58, 0xbfb8aa3b, v58
	v_exp_f32_e32 v58, v58
	s_nop 0
	v_add_f32_e32 v58, 1.0, v58
	v_rcp_f32_e32 v58, v58
	s_nop 0
	v_mul_f32_e32 v68, v22, v58
	v_add_f32_e32 v58, v68, v68
	v_cmp_nlt_f32_e32 vcc, s88, v58
	v_fma_f32 v150, v58, s72, 0.5
	v_fma_f32 v150, v58, v150, 1.0
	v_mul_f32_e64 v150, v150, -v58
	v_mul_f32_e32 v58, 0x3fb8aa3b, v58
	v_exp_f32_e32 v58, v58
	s_nop 0
	v_sub_f32_e32 v95, 1.0, v58
	v_cndmask_b32_e32 v95, v150, v95, vcc
	v_and_b32_e32 v58, 0xffff0000, v60
	v_add_f32_e32 v58, v15, v58
	v_mul_f32_e32 v58, 0xbfb8aa3b, v58
	v_exp_f32_e32 v58, v58
	s_nop 0
	v_add_f32_e32 v58, 1.0, v58
	v_rcp_f32_e32 v58, v58
	s_nop 0
	v_mul_f32_e32 v69, v23, v58
	v_add_f32_e32 v58, v69, v69
	v_cmp_nlt_f32_e32 vcc, s88, v58
	v_fma_f32 v150, v58, s72, 0.5
	v_fma_f32 v150, v58, v150, 1.0
	v_mul_f32_e64 v150, v150, -v58
	v_mul_f32_e32 v58, 0x3fb8aa3b, v58
	v_exp_f32_e32 v58, v58
	s_nop 0
	v_sub_f32_e32 v70, 1.0, v58
	v_cndmask_b32_e32 v70, v150, v70, vcc
	v_lshlrev_b32_e32 v58, 16, v61
	v_add_f32_e32 v58, v16, v58
	v_mul_f32_e32 v58, 0xbfb8aa3b, v58
	v_exp_f32_e32 v58, v58
	s_nop 0
	v_add_f32_e32 v58, 1.0, v58
	v_rcp_f32_e32 v58, v58
	s_nop 0
	v_mul_f32_e32 v58, v24, v58
	v_add_f32_e32 v59, v58, v58
	v_cmp_nlt_f32_e32 vcc, s88, v59
	v_fma_f32 v150, v59, s72, 0.5
	v_fma_f32 v150, v59, v150, 1.0
	v_mul_f32_e64 v150, v150, -v59
	v_mul_f32_e32 v59, 0x3fb8aa3b, v59
	v_exp_f32_e32 v59, v59
	s_nop 0
	v_sub_f32_e32 v60, 1.0, v59
	v_cndmask_b32_e32 v60, v150, v60, vcc
	v_and_b32_e32 v59, 0xffff0000, v61
	v_add_f32_e32 v59, v17, v59
	v_mul_f32_e32 v59, 0xbfb8aa3b, v59
	v_exp_f32_e32 v59, v59
	s_nop 0
	v_add_f32_e32 v59, 1.0, v59
	v_rcp_f32_e32 v59, v59
	s_nop 0
	v_mul_f32_e32 v59, v25, v59
	v_add_f32_e32 v71, v59, v59
	v_cmp_nlt_f32_e32 vcc, s88, v71
	v_fma_f32 v150, v71, s72, 0.5
	v_fma_f32 v150, v71, v150, 1.0
	v_mul_f32_e64 v150, v150, -v71
	v_mul_f32_e32 v61, 0x3fb8aa3b, v71
	v_exp_f32_e32 v61, v61
	s_nop 0
	v_sub_f32_e32 v61, 1.0, v61
	v_cndmask_b32_e32 v61, v150, v61, vcc
	s_branch .LBB0_738

; __device__ __forceinline__ unsigned cvt_pk_bf16(float lo, float hi) { f32x2_t v = {lo, hi}; bf16x2_t b = __builtin_convertvector(v, bf16x2_t); return __builtin_bit_cast(unsigned, b); }
; __device__ __forceinline__ void lru_coef(const u32x4 xw, const u32x4 aw, const u32x4 uw, const float (&sp)[8], const float (&bxv)[8], const float (&bav)[8], float (&l8)[8], float (&b8)[8]) {
;     const float gx[8] = {bflo(xw.x), bfhi(xw.x), bflo(xw.y), bfhi(xw.y), bflo(xw.z), bfhi(xw.z), bflo(xw.w), bfhi(xw.w)};
;     const float ga[8] = {bflo(aw.x), bfhi(aw.x), bflo(aw.y), bfhi(aw.y), bflo(aw.z), bfhi(aw.z), bflo(aw.w), bfhi(aw.w)};
;     const float uu[8] = {bflo(uw.x), bfhi(uw.x), bflo(uw.y), bfhi(uw.y), bflo(uw.z), bfhi(uw.z), bflo(uw.w), bfhi(uw.w)};
; #pragma unroll
;     for (int j = 0; j < 8; ++j) {
;         const float sx = __builtin_amdgcn_rcpf(1.0f + __builtin_amdgcn_exp2f(-(gx[j] + bxv[j]) * LOG2E));
;         const float sa = __builtin_amdgcn_rcpf(1.0f + __builtin_amdgcn_exp2f(-(ga[j] + bav[j]) * LOG2E));
;         const float la = sa * sp[j];
;         const float x2 = 2.0f * la;
;         const float om = (x2 > -0.02f) ? -x2 * (1.0f + x2 * (0.5f + x2 * 0.16666667f)) : 1.0f - __builtin_amdgcn_exp2f(x2 * LOG2E);
;         l8[j] = la * LOG2E; b8[j] = __builtin_amdgcn_sqrtf(fmaxf(om, 0.f)) * sx * uu[j];
;     }
; __global__ void __launch_bounds__(NT_, 2) fwd_mega(Args args) {
;     ...
;                 for (int st = 0; st < 64; ++st) {
;                     const u32x4 lw = *(const u32x4*)(LAb + (t0 + st) * 1024 + ch), bw = *(const u32x4*)(BVb + (t0 + st) * 1024 + ch), uw = *(const u32x4*)(UCb + (t0 + st) * 1024 + ch), gw4 = *(const u32x4*)(GYb + (t0 + st) * 1024 + ch);
;                     float l8[8], b8[8]; lru_coef(lw, bw, uw, sp, bxv, bav, l8, b8);
;                     const float g8[8] = {bflo(gw4.x), bfhi(gw4.x), bflo(gw4.y), bfhi(gw4.y), bflo(gw4.z), bfhi(gw4.z), bflo(gw4.w), bfhi(gw4.w)};
;                     float o[8];
; #pragma unroll
;                     for (int j = 0; j < 8; ++j) { h[j] = fast_exp2(l8[j]) * h[j] + b8[j]; o[j] = h[j] * g8[j]; }
;                     u32x4 w; w.x = cvt_pk_bf16(o[0], o[1]); w.y = cvt_pk_bf16(o[2], o[3]); w.z = cvt_pk_bf16(o[4], o[5]); w.w = cvt_pk_bf16(o[6], o[7]);
;                     *(u32x4*)(Ub + (t0 + st) * 1024 + ch) = w;
;                 }
.LBB0_855:
	v_lshlrev_b32_e32 v41, 16, v33
	v_add_f32_e32 v41, v4, v41
	v_mul_f32_e32 v41, 0xbfb8aa3b, v41
	v_exp_f32_e32 v41, v41
	v_mul_f32_e32 v69, 0x3fb8aa3b, v38
	v_max_f32_e32 v38, v67, v67
	v_max_f32_e32 v38, 0, v38
	v_add_f32_e32 v41, 1.0, v41
	v_rcp_f32_e32 v41, v41
	v_sqrt_f32_e32 v38, v38
	v_lshlrev_b32_e32 v68, 16, v37
	v_and_b32_e32 v67, 0xffff0000, v36
	v_lshlrev_b32_e32 v36, 16, v36
	v_mul_f32_e32 v38, v41, v38
	v_and_b32_e32 v41, 0xffff0000, v32
	v_add_f32_e32 v41, v3, v41
	v_mul_f32_e32 v41, 0xbfb8aa3b, v41
	v_exp_f32_e32 v41, v41
	v_mul_f32_e32 v38, v38, v68
	v_mul_f32_e32 v68, 0x3fb8aa3b, v40
	v_max_f32_e32 v40, v66, v66
	v_add_f32_e32 v41, 1.0, v41
	v_max_f32_e32 v40, 0, v40
	v_lshlrev_b32_e32 v32, 16, v32
	v_rcp_f32_e32 v41, v41
	v_sqrt_f32_e32 v40, v40
	v_add_f32_e32 v32, v2, v32
	v_mul_f32_e32 v32, 0xbfb8aa3b, v32
	v_exp_f32_e32 v32, v32
	v_mul_f32_e32 v40, v41, v40
	v_mul_f32_e32 v41, v40, v67
	v_max_f32_e32 v40, v65, v65
	v_add_f32_e32 v32, 1.0, v32
	v_max_f32_e32 v40, 0, v40
	v_rcp_f32_e32 v32, v32
	v_sqrt_f32_e32 v40, v40
	v_mul_f32_e32 v65, 0x3fb8aa3b, v39
	v_max_f32_e32 v39, v61, v61
	v_max_f32_e32 v39, 0, v39
	v_mul_f32_e32 v32, v32, v40
	v_mul_f32_e32 v40, v32, v36
	v_and_b32_e32 v32, 0xffff0000, v31
	v_add_f32_e32 v32, v9, v32
	v_mul_f32_e32 v32, 0xbfb8aa3b, v32
	v_exp_f32_e32 v32, v32
	v_lshlrev_b32_e32 v31, 16, v31
	v_sqrt_f32_e32 v39, v39
	v_add_f32_e32 v31, v8, v31
	v_add_f32_e32 v32, 1.0, v32
	v_rcp_f32_e32 v32, v32
	v_mul_f32_e32 v31, 0xbfb8aa3b, v31
	v_exp_f32_e32 v31, v31
	v_and_b32_e32 v36, 0xffff0000, v35
	v_mul_f32_e32 v32, v32, v39
	v_mul_f32_e32 v61, v32, v36
	v_lshlrev_b32_e32 v32, 16, v35
	v_max_f32_e32 v35, v60, v60
	v_add_f32_e32 v31, 1.0, v31
	v_max_f32_e32 v35, 0, v35
	v_rcp_f32_e32 v31, v31
	v_sqrt_f32_e32 v35, v35
	v_max_f32_e32 v39, v56, v56
	v_max_f32_e32 v39, 0, v39
	v_sqrt_f32_e32 v39, v39
	v_mul_f32_e32 v31, v31, v35
	v_mul_f32_e32 v60, v31, v32
	v_and_b32_e32 v31, 0xffff0000, v30
	v_add_f32_e32 v31, v7, v31
	v_mul_f32_e32 v31, 0xbfb8aa3b, v31
	v_exp_f32_e32 v31, v31
	v_lshlrev_b32_e32 v30, 16, v30
	v_add_f32_e32 v30, v6, v30
	v_mul_f32_e32 v30, 0xbfb8aa3b, v30
	v_add_f32_e32 v31, 1.0, v31
	v_rcp_f32_e32 v31, v31
	v_exp_f32_e32 v30, v30
	v_and_b32_e32 v32, 0xffff0000, v34
	v_mul_f32_e32 v35, 0x3fb8aa3b, v55
	v_mul_f32_e32 v31, v31, v39
	v_mul_f32_e32 v31, v31, v32
	v_lshlrev_b32_e32 v32, 16, v34
	v_max_f32_e32 v34, v54, v54
	v_add_f32_e32 v30, 1.0, v30
	v_max_f32_e32 v34, 0, v34
	v_rcp_f32_e32 v30, v30
	v_sqrt_f32_e32 v34, v34
	v_mul_f32_e32 v0, 0x3fb8aa3b, v0
	v_mul_f32_e32 v36, 0x3fb8aa3b, v57
	v_mul_f32_e32 v64, 0x3fb8aa3b, v64
	v_mul_f32_e32 v30, v30, v34
	v_mul_f32_e32 v30, v30, v32
	v_and_b32_e32 v32, 0xffff0000, v33
	v_add_f32_e32 v32, v5, v32
	v_mul_f32_e32 v32, 0xbfb8aa3b, v32
	v_exp_f32_e32 v32, v32
	v_max_f32_e32 v34, v63, v63
	v_max_f32_e32 v34, 0, v34
	v_sqrt_f32_e32 v34, v34
	v_add_f32_e32 v32, 1.0, v32
	v_rcp_f32_e32 v32, v32
	v_and_b32_e32 v33, 0xffff0000, v37
	v_mul_f32_e32 v37, 0x3fb8aa3b, v62
	s_add_u32 s6, s6, 0x1000
	v_mul_f32_e32 v32, v32, v34
	v_mul_f32_e32 v39, v32, v33
	v_exp_f32_e32 v32, v0
	v_exp_f32_e32 v33, v35
	s_waitcnt vmcnt(0) lgkmcnt(0)
	v_lshlrev_b32_e32 v34, 16, v26
	v_and_b32_e32 v35, 0xffff0000, v26
	v_lshlrev_b32_e32 v26, 16, v27
	v_pk_fma_f32 v[50:51], v[32:33], v[50:51], v[30:31]
	v_exp_f32_e32 v32, v36
	v_exp_f32_e32 v33, v65
	v_and_b32_e32 v27, 0xffff0000, v27
	v_pk_mul_f32 v[30:31], v[50:51], v[34:35]
	v_lshlrev_b32_e32 v34, 16, v28
	v_pk_fma_f32 v[48:49], v[32:33], v[48:49], v[60:61]
	v_and_b32_e32 v35, 0xffff0000, v28
	v_pk_mul_f32 v[32:33], v[48:49], v[26:27]
	v_exp_f32_e32 v26, v64
	v_exp_f32_e32 v27, v68
	v_lshlrev_b32_e32 v28, 16, v29
	v_and_b32_e32 v29, 0xffff0000, v29
	s_addc_u32 s7, s7, 0
	v_pk_fma_f32 v[46:47], v[26:27], v[46:47], v[40:41]
	v_exp_f32_e32 v26, v69
	v_exp_f32_e32 v27, v37
	v_pk_mul_f32 v[34:35], v[46:47], v[34:35]
	s_cmp_eq_u32 s6, 0x20000
	v_pk_fma_f32 v[44:45], v[26:27], v[44:45], v[38:39]
	s_nop 0
	v_pk_mul_f32 v[36:37], v[44:45], v[28:29]
	v_cvt_pk_bf16_f32 v26, v30, v31
	v_cvt_pk_bf16_f32 v27, v32, v33
	v_cvt_pk_bf16_f32 v28, v34, v35
	v_cvt_pk_bf16_f32 v29, v36, v37
	flat_store_dwordx4 v[52:53], v[26:29] offset:2048
	s_cbranch_scc1 .LBB0_849
; __device__ __forceinline__ float bflo(unsigned w) { return __uint_as_float(w << 16); }
; __device__ __forceinline__ float bfhi(unsigned w) { return __uint_as_float(w & 0xffff0000u); }
; __device__ __forceinline__ float fast_exp2(float x) { return __builtin_amdgcn_exp2f(x); }
; __device__ __forceinline__ void lru_coef(const u32x4 xw, const u32x4 aw, const u32x4 uw, const float (&sp)[8], const float (&bxv)[8], const float (&bav)[8], float (&l8)[8], float (&b8)[8]) {
;     const float gx[8] = {bflo(xw.x), bfhi(xw.x), bflo(xw.y), bfhi(xw.y), bflo(xw.z), bfhi(xw.z), bflo(xw.w), bfhi(xw.w)};
;     const float ga[8] = {bflo(aw.x), bfhi(aw.x), bflo(aw.y), bfhi(aw.y), bflo(aw.z), bfhi(aw.z), bflo(aw.w), bfhi(aw.w)};
;     const float uu[8] = {bflo(uw.x), bfhi(uw.x), bflo(uw.y), bfhi(uw.y), bflo(uw.z), bfhi(uw.z), bflo(uw.w), bfhi(uw.w)};
; #pragma unroll
;     for (int j = 0; j < 8; ++j) {
;         const float sx = __builtin_amdgcn_rcpf(1.0f + __builtin_amdgcn_exp2f(-(gx[j] + bxv[j]) * LOG2E));
;         const float sa = __builtin_amdgcn_rcpf(1.0f + __builtin_amdgcn_exp2f(-(ga[j] + bav[j]) * LOG2E));
;         const float la = sa * sp[j];
;         const float x2 = 2.0f * la;
;         const float om = (x2 > -0.02f) ? -x2 * (1.0f + x2 * (0.5f + x2 * 0.16666667f)) : 1.0f - __builtin_amdgcn_exp2f(x2 * LOG2E);
;         l8[j] = la * LOG2E; b8[j] = __builtin_amdgcn_sqrtf(fmaxf(om, 0.f)) * sx * uu[j];
;     }
; }
; __global__ void __launch_bounds__(NT_, 2) fwd_mega(Args args) {
;     ...
; #pragma unroll 2
;                 for (int st = 0; st < 64; ++st) {
;                     const u32x4 lw = *(const u32x4*)(LAb + (t0 + st) * 1024 + ch), bw = *(const u32x4*)(BVb + (t0 + st) * 1024 + ch), uw = *(const u32x4*)(UCb + (t0 + st) * 1024 + ch), gw4 = *(const u32x4*)(GYb + (t0 + st) * 1024 + ch);
;                     float l8[8], b8[8]; lru_coef(lw, bw, uw, sp, bxv, bav, l8, b8);
;                     const float g8[8] = {bflo(gw4.x), bfhi(gw4.x), bflo(gw4.y), bfhi(gw4.y), bflo(gw4.z), bfhi(gw4.z), bflo(gw4.w), bfhi(gw4.w)};
;                     float o[8];
; #pragma unroll
;                     for (int j = 0; j < 8; ++j) { h[j] = fast_exp2(l8[j]) * h[j] + b8[j]; o[j] = h[j] * g8[j]; }
.LBB0_856:
	v_lshl_add_u64 v[54:55], v[42:43], 0, s[6:7]
	v_add_co_u32_e32 v26, vcc, 0x28000000, v54
	s_nop 1
	v_addc_co_u32_e32 v27, vcc, 0, v55, vcc
	v_add_co_u32_e32 v28, vcc, 0x8000000, v54
	s_nop 1
	v_addc_co_u32_e32 v29, vcc, 0, v55, vcc
	flat_load_dwordx4 v[38:41], v[28:29]
	flat_load_dwordx4 v[30:33], v[26:27]
	v_add_co_u32_e32 v56, vcc, s80, v54
	s_waitcnt vmcnt(0) lgkmcnt(0)
	v_lshlrev_b32_e32 v0, 16, v38
	v_addc_co_u32_e32 v57, vcc, 0, v55, vcc
	v_add_co_u32_e32 v26, vcc, 0x10000000, v54
	v_add_f32_e32 v0, v14, v0
	s_nop 0
	v_addc_co_u32_e32 v27, vcc, 0, v55, vcc
	flat_load_dwordx4 v[34:37], v[56:57]
	s_nop 0
	flat_load_dwordx4 v[26:29], v[26:27]
	v_mul_f32_e32 v0, 0xbfb8aa3b, v0
	v_exp_f32_e32 v0, v0
	s_nop 0
	v_add_f32_e32 v0, 1.0, v0
	v_rcp_f32_e32 v0, v0
	s_nop 0
	v_mul_f32_e32 v0, v18, v0
	v_add_f32_e32 v53, v0, v0
	v_cmp_nlt_f32_e32 vcc, s88, v53
	v_fma_f32 v150, v53, s72, 0.5
	v_fma_f32 v150, v53, v150, 1.0
	v_mul_f32_e64 v150, v150, -v53
	v_mul_f32_e32 v52, 0x3fb8aa3b, v53
	v_exp_f32_e32 v52, v52
	s_nop 0
	v_sub_f32_e32 v52, 1.0, v52
	v_cndmask_b32_e32 v52, v150, v52, vcc
	v_and_b32_e32 v38, 0xffff0000, v38
	v_add_f32_e32 v38, v15, v38
	v_mul_f32_e32 v38, 0xbfb8aa3b, v38
	v_exp_f32_e32 v38, v38
	s_nop 0
	v_add_f32_e32 v38, 1.0, v38
	v_rcp_f32_e32 v38, v38
	s_nop 0
	v_mul_f32_e32 v38, v19, v38
	v_add_f32_e32 v60, v38, v38
	v_cmp_nlt_f32_e32 vcc, s88, v60
	v_fma_f32 v150, v60, s72, 0.5
	v_fma_f32 v150, v60, v150, 1.0
	v_mul_f32_e64 v150, v150, -v60
	v_mul_f32_e32 v53, 0x3fb8aa3b, v60
	v_exp_f32_e32 v53, v53
	s_nop 0
	v_sub_f32_e32 v53, 1.0, v53
	v_cndmask_b32_e32 v53, v150, v53, vcc
	v_lshlrev_b32_e32 v60, 16, v39
	v_add_f32_e32 v60, v16, v60
	v_mul_f32_e32 v60, 0xbfb8aa3b, v60
	v_exp_f32_e32 v60, v60
	s_nop 0
	v_add_f32_e32 v60, 1.0, v60
	v_rcp_f32_e32 v60, v60
	s_nop 0
	v_mul_f32_e32 v60, v20, v60
	v_add_f32_e32 v62, v60, v60
	v_cmp_nlt_f32_e32 vcc, s88, v62
	v_fma_f32 v150, v62, s72, 0.5
	v_fma_f32 v150, v62, v150, 1.0
	v_mul_f32_e64 v150, v150, -v62
	v_mul_f32_e32 v61, 0x3fb8aa3b, v62
	v_exp_f32_e32 v61, v61
	s_nop 0
	v_sub_f32_e32 v61, 1.0, v61
	v_cndmask_b32_e32 v61, v150, v61, vcc
	v_and_b32_e32 v39, 0xffff0000, v39
	v_add_f32_e32 v39, v17, v39
	v_mul_f32_e32 v39, 0xbfb8aa3b, v39
	v_exp_f32_e32 v39, v39
	s_nop 0
	v_add_f32_e32 v39, 1.0, v39
	v_rcp_f32_e32 v39, v39
	s_nop 0
	v_mul_f32_e32 v39, v21, v39
	v_add_f32_e32 v63, v39, v39
	v_cmp_nlt_f32_e32 vcc, s88, v63
	v_fma_f32 v150, v63, s72, 0.5
	v_fma_f32 v150, v63, v150, 1.0
	v_mul_f32_e64 v150, v150, -v63
	v_mul_f32_e32 v62, 0x3fb8aa3b, v63
	v_exp_f32_e32 v62, v62
	s_nop 0
	v_sub_f32_e32 v62, 1.0, v62
	v_cndmask_b32_e32 v62, v150, v62, vcc
	v_lshlrev_b32_e32 v63, 16, v40
	v_add_f32_e32 v63, v10, v63
	v_mul_f32_e32 v63, 0xbfb8aa3b, v63
	v_exp_f32_e32 v63, v63
	s_nop 0
	v_add_f32_e32 v63, 1.0, v63
	v_rcp_f32_e32 v63, v63
	s_nop 0
	v_mul_f32_e32 v63, v22, v63
	v_add_f32_e32 v65, v63, v63
	v_cmp_nlt_f32_e32 vcc, s88, v65
	v_fma_f32 v150, v65, s72, 0.5
	v_fma_f32 v150, v65, v150, 1.0
	v_mul_f32_e64 v150, v150, -v65
	v_mul_f32_e32 v64, 0x3fb8aa3b, v65
	v_exp_f32_e32 v64, v64
	s_nop 0
	v_sub_f32_e32 v64, 1.0, v64
	v_cndmask_b32_e32 v64, v150, v64, vcc
	v_and_b32_e32 v40, 0xffff0000, v40
	v_add_f32_e32 v40, v11, v40
	v_mul_f32_e32 v40, 0xbfb8aa3b, v40
	v_exp_f32_e32 v40, v40
	s_nop 0
	v_add_f32_e32 v40, 1.0, v40
	v_rcp_f32_e32 v40, v40
	s_nop 0
	v_mul_f32_e32 v65, v23, v40
	v_add_f32_e32 v40, v65, v65
	v_cmp_nlt_f32_e32 vcc, s88, v40
	v_fma_f32 v150, v40, s72, 0.5
	v_fma_f32 v150, v40, v150, 1.0
	v_mul_f32_e64 v150, v150, -v40
	v_mul_f32_e32 v40, 0x3fb8aa3b, v40
	v_exp_f32_e32 v40, v40
	s_nop 0
	v_sub_f32_e32 v66, 1.0, v40
	v_cndmask_b32_e32 v66, v150, v66, vcc
	v_lshlrev_b32_e32 v40, 16, v41
	v_add_f32_e32 v40, v12, v40
	v_mul_f32_e32 v40, 0xbfb8aa3b, v40
	v_exp_f32_e32 v40, v40
	s_nop 0
	v_add_f32_e32 v40, 1.0, v40
	v_rcp_f32_e32 v40, v40
	s_nop 0
	v_mul_f32_e32 v67, v24, v40
	v_add_f32_e32 v40, v67, v67
	v_cmp_nlt_f32_e32 vcc, s88, v40
	v_fma_f32 v150, v40, s72, 0.5
	v_fma_f32 v150, v40, v150, 1.0
	v_mul_f32_e64 v150, v150, -v40
	v_mul_f32_e32 v40, 0x3fb8aa3b, v40
	v_exp_f32_e32 v40, v40
	s_nop 0
	v_sub_f32_e32 v68, 1.0, v40
	v_cndmask_b32_e32 v68, v150, v68, vcc
	v_and_b32_e32 v40, 0xffff0000, v41
	v_add_f32_e32 v40, v13, v40
	v_mul_f32_e32 v40, 0xbfb8aa3b, v40
	v_exp_f32_e32 v40, v40
	s_nop 0
	v_add_f32_e32 v40, 1.0, v40
	v_rcp_f32_e32 v40, v40
	s_nop 0
	v_mul_f32_e32 v40, v25, v40
	v_add_f32_e32 v69, v40, v40
	v_cmp_nlt_f32_e32 vcc, s88, v69
	v_fma_f32 v150, v69, s72, 0.5
	v_fma_f32 v150, v69, v150, 1.0
	v_mul_f32_e64 v150, v150, -v69
	v_mul_f32_e32 v41, 0x3fb8aa3b, v69
	v_exp_f32_e32 v41, v41
	s_nop 0
	v_sub_f32_e32 v41, 1.0, v41
	v_cndmask_b32_e32 v41, v150, v41, vcc
	v_lshlrev_b32_e32 v69, 16, v33
	v_add_f32_e32 v69, v4, v69
	v_mul_f32_e32 v69, 0xbfb8aa3b, v69
	v_exp_f32_e32 v69, v69
	v_max_f32_e32 v68, v68, v68
	v_max_f32_e32 v68, 0, v68
	v_sqrt_f32_e32 v68, v68
	v_add_f32_e32 v69, 1.0, v69
	v_rcp_f32_e32 v69, v69
	v_mul_f32_e32 v71, 0x3fb8aa3b, v65
	v_max_f32_e32 v65, v66, v66
	v_mul_f32_e32 v66, 0x3fb8aa3b, v63
	v_mul_f32_e32 v68, v69, v68
	v_and_b32_e32 v69, 0xffff0000, v32
	v_lshlrev_b32_e32 v32, 16, v32
	v_add_f32_e32 v32, v2, v32
	v_mul_f32_e32 v32, 0xbfb8aa3b, v32
	v_exp_f32_e32 v32, v32
	v_max_f32_e32 v63, v64, v64
	v_max_f32_e32 v63, 0, v63
	v_sqrt_f32_e32 v63, v63
	v_add_f32_e32 v32, 1.0, v32
	v_rcp_f32_e32 v32, v32
	s_waitcnt vmcnt(0) lgkmcnt(0)
; __device__ __forceinline__ unsigned cvt_pk_bf16(float lo, float hi) { f32x2_t v = {lo, hi}; bf16x2_t b = __builtin_convertvector(v, bf16x2_t); return __builtin_bit_cast(unsigned, b); }
; __device__ __forceinline__ float bflo(unsigned w) { return __uint_as_float(w << 16); }
; __device__ __forceinline__ float bfhi(unsigned w) { return __uint_as_float(w & 0xffff0000u); }
; __device__ __forceinline__ float fast_exp2(float x) { return __builtin_amdgcn_exp2f(x); }
; __device__ __forceinline__ void lru_coef(const u32x4 xw, const u32x4 aw, const u32x4 uw, const float (&sp)[8], const float (&bxv)[8], const float (&bav)[8], float (&l8)[8], float (&b8)[8]) {
;     ...
;         l8[j] = la * LOG2E; b8[j] = __builtin_amdgcn_sqrtf(fmaxf(om, 0.f)) * sx * uu[j];
;     }
; __global__ void __launch_bounds__(NT_, 2) fwd_mega(Args args) {
;     ...
;                 for (int st = 0; st < 64; ++st) {
;                     const u32x4 lw = *(const u32x4*)(LAb + (t0 + st) * 1024 + ch), bw = *(const u32x4*)(BVb + (t0 + st) * 1024 + ch), uw = *(const u32x4*)(UCb + (t0 + st) * 1024 + ch), gw4 = *(const u32x4*)(GYb + (t0 + st) * 1024 + ch);
;                     float l8[8], b8[8]; lru_coef(lw, bw, uw, sp, bxv, bav, l8, b8);
;                     const float g8[8] = {bflo(gw4.x), bfhi(gw4.x), bflo(gw4.y), bfhi(gw4.y), bflo(gw4.z), bfhi(gw4.z), bflo(gw4.w), bfhi(gw4.w)};
;                     float o[8];
; #pragma unroll
;                     for (int j = 0; j < 8; ++j) { h[j] = fast_exp2(l8[j]) * h[j] + b8[j]; o[j] = h[j] * g8[j]; }
;                     u32x4 w; w.x = cvt_pk_bf16(o[0], o[1]); w.y = cvt_pk_bf16(o[2], o[3]); w.z = cvt_pk_bf16(o[4], o[5]); w.w = cvt_pk_bf16(o[6], o[7]);
;                     *(u32x4*)(Ub + (t0 + st) * 1024 + ch) = w;
	v_lshlrev_b32_e32 v70, 16, v37
	v_mul_f32_e32 v68, v68, v70
	v_and_b32_e32 v70, 0xffff0000, v36
	v_lshlrev_b32_e32 v36, 16, v36
	v_mul_f32_e32 v32, v32, v63
	v_mul_f32_e32 v64, v32, v36
	v_and_b32_e32 v32, 0xffff0000, v31
	v_add_f32_e32 v32, v9, v32
	v_mul_f32_e32 v32, 0xbfb8aa3b, v32
	v_exp_f32_e32 v32, v32
	v_max_f32_e32 v62, v62, v62
	v_max_f32_e32 v62, 0, v62
	v_lshlrev_b32_e32 v31, 16, v31
	v_add_f32_e32 v32, 1.0, v32
	v_rcp_f32_e32 v32, v32
	v_sqrt_f32_e32 v62, v62
	v_add_f32_e32 v31, v8, v31
	v_mul_f32_e32 v31, 0xbfb8aa3b, v31
	v_exp_f32_e32 v31, v31
	v_and_b32_e32 v36, 0xffff0000, v35
	v_mul_f32_e32 v32, v32, v62
	v_mul_f32_e32 v63, v32, v36
	v_lshlrev_b32_e32 v32, 16, v35
	v_max_f32_e32 v35, v61, v61
	v_add_f32_e32 v31, 1.0, v31
	v_max_f32_e32 v35, 0, v35
	v_rcp_f32_e32 v31, v31
	v_sqrt_f32_e32 v35, v35
	v_add_f32_e32 v69, v3, v69
	v_mul_f32_e32 v69, 0xbfb8aa3b, v69
	v_exp_f32_e32 v69, v69
	v_mul_f32_e32 v31, v31, v35
	v_mul_f32_e32 v62, v31, v32
	v_and_b32_e32 v31, 0xffff0000, v30
	v_add_f32_e32 v31, v7, v31
	v_mul_f32_e32 v31, 0xbfb8aa3b, v31
	v_exp_f32_e32 v31, v31
	v_mul_f32_e32 v35, 0x3fb8aa3b, v38
	v_max_f32_e32 v38, v53, v53
	v_max_f32_e32 v38, 0, v38
	v_add_f32_e32 v31, 1.0, v31
	v_lshlrev_b32_e32 v30, 16, v30
	v_rcp_f32_e32 v31, v31
	v_sqrt_f32_e32 v38, v38
	v_add_f32_e32 v30, v6, v30
	v_mul_f32_e32 v30, 0xbfb8aa3b, v30
	v_exp_f32_e32 v30, v30
	v_and_b32_e32 v32, 0xffff0000, v34
	v_mul_f32_e32 v31, v31, v38
	v_mul_f32_e32 v31, v31, v32
	v_lshlrev_b32_e32 v32, 16, v34
	v_max_f32_e32 v34, v52, v52
	v_add_f32_e32 v30, 1.0, v30
	v_max_f32_e32 v34, 0, v34
	v_rcp_f32_e32 v30, v30
	v_sqrt_f32_e32 v34, v34
	v_add_f32_e32 v69, 1.0, v69
	v_max_f32_e32 v65, 0, v65
	v_rcp_f32_e32 v69, v69
	v_mul_f32_e32 v30, v30, v34
	v_mul_f32_e32 v30, v30, v32
	v_and_b32_e32 v32, 0xffff0000, v33
	v_add_f32_e32 v32, v5, v32
	v_mul_f32_e32 v32, 0xbfb8aa3b, v32
	v_exp_f32_e32 v32, v32
	v_max_f32_e32 v34, v41, v41
	v_max_f32_e32 v34, 0, v34
	v_sqrt_f32_e32 v34, v34
	v_add_f32_e32 v32, 1.0, v32
	v_rcp_f32_e32 v32, v32
	v_sqrt_f32_e32 v65, v65
	v_mul_f32_e32 v0, 0x3fb8aa3b, v0
	v_and_b32_e32 v33, 0xffff0000, v37
	v_mul_f32_e32 v32, v32, v34
	v_mul_f32_e32 v65, v69, v65
	v_mul_f32_e32 v69, v32, v33
	v_exp_f32_e32 v32, v0
	v_exp_f32_e32 v33, v35
	v_mul_f32_e32 v39, 0x3fb8aa3b, v39
	v_mul_f32_e32 v36, 0x3fb8aa3b, v60
	v_lshlrev_b32_e32 v34, 16, v26
	v_pk_fma_f32 v[50:51], v[32:33], v[50:51], v[30:31]
	v_exp_f32_e32 v32, v36
	v_exp_f32_e32 v33, v39
	v_and_b32_e32 v35, 0xffff0000, v26
	v_lshlrev_b32_e32 v26, 16, v27
	v_and_b32_e32 v27, 0xffff0000, v27
	v_pk_fma_f32 v[48:49], v[32:33], v[48:49], v[62:63]
	v_mul_f32_e32 v67, 0x3fb8aa3b, v67
	v_pk_mul_f32 v[32:33], v[48:49], v[26:27]
	v_exp_f32_e32 v26, v66
	v_exp_f32_e32 v27, v71
	v_mul_f32_e32 v65, v65, v70
	v_mul_f32_e32 v37, 0x3fb8aa3b, v40
	v_pk_mul_f32 v[30:31], v[50:51], v[34:35]
	v_pk_fma_f32 v[46:47], v[26:27], v[46:47], v[64:65]
	v_exp_f32_e32 v26, v67
	v_exp_f32_e32 v27, v37
	v_lshlrev_b32_e32 v34, 16, v28
	v_and_b32_e32 v35, 0xffff0000, v28
	v_lshlrev_b32_e32 v28, 16, v29
	v_and_b32_e32 v29, 0xffff0000, v29
	v_pk_fma_f32 v[44:45], v[26:27], v[44:45], v[68:69]
	s_brev_b32 s8, 24
	v_pk_mul_f32 v[34:35], v[46:47], v[34:35]
	v_pk_mul_f32 v[36:37], v[44:45], v[28:29]
	v_add_co_u32_e32 v52, vcc, s8, v54
	v_cvt_pk_bf16_f32 v26, v30, v31
	v_cvt_pk_bf16_f32 v27, v32, v33
	v_cvt_pk_bf16_f32 v28, v34, v35
	v_cvt_pk_bf16_f32 v29, v36, v37
	v_addc_co_u32_e32 v53, vcc, 0, v55, vcc
	s_brev_b32 s8, 20
	flat_store_dwordx4 v[52:53], v[26:29]
	s_nop 1
	v_add_co_u32_e32 v26, vcc, s8, v54
	s_brev_b32 s8, 16
	s_nop 0
	v_addc_co_u32_e32 v27, vcc, 0, v55, vcc
	flat_load_dwordx4 v[30:33], v[26:27] offset:2048
	v_add_co_u32_e32 v26, vcc, s8, v54
	s_nop 1
	v_addc_co_u32_e32 v27, vcc, 0, v55, vcc
	flat_load_dwordx4 v[38:41], v[26:27] offset:2048
	flat_load_dwordx4 v[34:37], v[56:57] offset:2048
	v_add_co_u32_e32 v26, vcc, 0x10000000, v54
	s_waitcnt vmcnt(0) lgkmcnt(0)
; __device__ __forceinline__ float bflo(unsigned w) { return __uint_as_float(w << 16); }
; __device__ __forceinline__ float bfhi(unsigned w) { return __uint_as_float(w & 0xffff0000u); }
; __device__ __forceinline__ void lru_coef(const u32x4 xw, const u32x4 aw, const u32x4 uw, const float (&sp)[8], const float (&bxv)[8], const float (&bav)[8], float (&l8)[8], float (&b8)[8]) {
;     const float gx[8] = {bflo(xw.x), bfhi(xw.x), bflo(xw.y), bfhi(xw.y), bflo(xw.z), bfhi(xw.z), bflo(xw.w), bfhi(xw.w)};
;     const float ga[8] = {bflo(aw.x), bfhi(aw.x), bflo(aw.y), bfhi(aw.y), bflo(aw.z), bfhi(aw.z), bflo(aw.w), bfhi(aw.w)};
;     const float uu[8] = {bflo(uw.x), bfhi(uw.x), bflo(uw.y), bfhi(uw.y), bflo(uw.z), bfhi(uw.z), bflo(uw.w), bfhi(uw.w)};
; #pragma unroll
;     for (int j = 0; j < 8; ++j) {
;         const float sx = __builtin_amdgcn_rcpf(1.0f + __builtin_amdgcn_exp2f(-(gx[j] + bxv[j]) * LOG2E));
;         const float sa = __builtin_amdgcn_rcpf(1.0f + __builtin_amdgcn_exp2f(-(ga[j] + bav[j]) * LOG2E));
;         const float la = sa * sp[j];
;         const float x2 = 2.0f * la;
;         const float om = (x2 > -0.02f) ? -x2 * (1.0f + x2 * (0.5f + x2 * 0.16666667f)) : 1.0f - __builtin_amdgcn_exp2f(x2 * LOG2E);
;         l8[j] = la * LOG2E; b8[j] = __builtin_amdgcn_sqrtf(fmaxf(om, 0.f)) * sx * uu[j];
;     }
; }
	v_lshlrev_b32_e32 v0, 16, v38
	v_addc_co_u32_e32 v27, vcc, 0, v55, vcc
	flat_load_dwordx4 v[26:29], v[26:27] offset:2048
	v_add_f32_e32 v0, v14, v0
	v_mul_f32_e32 v0, 0xbfb8aa3b, v0
	v_exp_f32_e32 v0, v0
	s_nop 0
	v_add_f32_e32 v0, 1.0, v0
	v_rcp_f32_e32 v0, v0
	s_nop 0
	v_mul_f32_e32 v0, v18, v0
	v_add_f32_e32 v55, v0, v0
	v_cmp_nlt_f32_e32 vcc, s88, v55
	v_fma_f32 v150, v55, s72, 0.5
	v_fma_f32 v150, v55, v150, 1.0
	v_mul_f32_e64 v150, v150, -v55
	v_mul_f32_e32 v54, 0x3fb8aa3b, v55
	v_exp_f32_e32 v54, v54
	s_nop 0
	v_sub_f32_e32 v54, 1.0, v54
	v_cndmask_b32_e32 v54, v150, v54, vcc
	v_and_b32_e32 v38, 0xffff0000, v38
	v_add_f32_e32 v38, v15, v38
	v_mul_f32_e32 v38, 0xbfb8aa3b, v38
	v_exp_f32_e32 v38, v38
	s_nop 0
	v_add_f32_e32 v38, 1.0, v38
	v_rcp_f32_e32 v38, v38
	s_nop 0
	v_mul_f32_e32 v55, v19, v38
	v_add_f32_e32 v38, v55, v55
	v_cmp_nlt_f32_e32 vcc, s88, v38
	v_fma_f32 v150, v38, s72, 0.5
	v_fma_f32 v150, v38, v150, 1.0
	v_mul_f32_e64 v150, v150, -v38
	v_mul_f32_e32 v38, 0x3fb8aa3b, v38
	v_exp_f32_e32 v38, v38
	s_nop 0
	v_sub_f32_e32 v56, 1.0, v38
	v_cndmask_b32_e32 v56, v150, v56, vcc
	v_lshlrev_b32_e32 v38, 16, v39
	v_add_f32_e32 v38, v16, v38
	v_mul_f32_e32 v38, 0xbfb8aa3b, v38
	v_exp_f32_e32 v38, v38
	s_nop 0
	v_add_f32_e32 v38, 1.0, v38
	v_rcp_f32_e32 v38, v38
	s_nop 0
	v_mul_f32_e32 v57, v20, v38
	v_add_f32_e32 v38, v57, v57
	v_cmp_nlt_f32_e32 vcc, s88, v38
	v_fma_f32 v150, v38, s72, 0.5
	v_fma_f32 v150, v38, v150, 1.0
	v_mul_f32_e64 v150, v150, -v38
	v_mul_f32_e32 v38, 0x3fb8aa3b, v38
	v_exp_f32_e32 v38, v38
	s_nop 0
	v_sub_f32_e32 v60, 1.0, v38
	v_cndmask_b32_e32 v60, v150, v60, vcc
	v_and_b32_e32 v38, 0xffff0000, v39
	v_add_f32_e32 v38, v17, v38
	v_mul_f32_e32 v38, 0xbfb8aa3b, v38
	v_exp_f32_e32 v38, v38
	s_nop 0
	v_add_f32_e32 v38, 1.0, v38
	v_rcp_f32_e32 v38, v38
	s_nop 0
	v_mul_f32_e32 v39, v21, v38
	v_add_f32_e32 v38, v39, v39
	v_cmp_nlt_f32_e32 vcc, s88, v38
	v_fma_f32 v150, v38, s72, 0.5
	v_fma_f32 v150, v38, v150, 1.0
	v_mul_f32_e64 v150, v150, -v38
	v_mul_f32_e32 v38, 0x3fb8aa3b, v38
	v_exp_f32_e32 v38, v38
	s_nop 0
	v_sub_f32_e32 v61, 1.0, v38
	v_cndmask_b32_e32 v61, v150, v61, vcc
	v_lshlrev_b32_e32 v38, 16, v40
	v_add_f32_e32 v38, v10, v38
	v_mul_f32_e32 v38, 0xbfb8aa3b, v38
	v_exp_f32_e32 v38, v38
	s_nop 0
	v_add_f32_e32 v38, 1.0, v38
	v_rcp_f32_e32 v38, v38
	s_nop 0
	v_mul_f32_e32 v64, v22, v38
	v_add_f32_e32 v38, v64, v64
	v_cmp_nlt_f32_e32 vcc, s88, v38
	v_fma_f32 v150, v38, s72, 0.5
	v_fma_f32 v150, v38, v150, 1.0
	v_mul_f32_e64 v150, v150, -v38
	v_mul_f32_e32 v38, 0x3fb8aa3b, v38
	v_exp_f32_e32 v38, v38
	s_nop 0
	v_sub_f32_e32 v65, 1.0, v38
	v_cndmask_b32_e32 v65, v150, v65, vcc
	v_and_b32_e32 v38, 0xffff0000, v40
	v_add_f32_e32 v38, v11, v38
	v_mul_f32_e32 v38, 0xbfb8aa3b, v38
	v_exp_f32_e32 v38, v38
	s_nop 0
	v_add_f32_e32 v38, 1.0, v38
	v_rcp_f32_e32 v38, v38
	s_nop 0
	v_mul_f32_e32 v40, v23, v38
	v_add_f32_e32 v38, v40, v40
	v_cmp_nlt_f32_e32 vcc, s88, v38
	v_fma_f32 v150, v38, s72, 0.5
	v_fma_f32 v150, v38, v150, 1.0
	v_mul_f32_e64 v150, v150, -v38
	v_mul_f32_e32 v38, 0x3fb8aa3b, v38
	v_exp_f32_e32 v38, v38
	s_nop 0
	v_sub_f32_e32 v66, 1.0, v38
	v_cndmask_b32_e32 v66, v150, v66, vcc
	v_lshlrev_b32_e32 v38, 16, v41
	v_add_f32_e32 v38, v12, v38
	v_mul_f32_e32 v38, 0xbfb8aa3b, v38
	v_exp_f32_e32 v38, v38
	s_nop 0
	v_add_f32_e32 v38, 1.0, v38
	v_rcp_f32_e32 v38, v38
	s_nop 0
	v_mul_f32_e32 v38, v24, v38
	v_add_f32_e32 v62, v38, v38
	v_cmp_nlt_f32_e32 vcc, s88, v62
	v_fma_f32 v150, v62, s72, 0.5
	v_fma_f32 v150, v62, v150, 1.0
	v_mul_f32_e64 v150, v150, -v62
	v_mul_f32_e32 v62, 0x3fb8aa3b, v62
	v_exp_f32_e32 v62, v62
	s_nop 0
	v_sub_f32_e32 v67, 1.0, v62
	v_cndmask_b32_e32 v67, v150, v67, vcc
	v_and_b32_e32 v41, 0xffff0000, v41
	v_add_f32_e32 v41, v13, v41
	v_mul_f32_e32 v41, 0xbfb8aa3b, v41
	v_exp_f32_e32 v41, v41
	s_nop 0
	v_add_f32_e32 v41, 1.0, v41
	v_rcp_f32_e32 v41, v41
	s_nop 0
	v_mul_f32_e32 v62, v25, v41
	v_add_f32_e32 v41, v62, v62
	v_cmp_nlt_f32_e32 vcc, s88, v41
	v_fma_f32 v150, v41, s72, 0.5
	v_fma_f32 v150, v41, v150, 1.0
	v_mul_f32_e64 v150, v150, -v41
	v_mul_f32_e32 v41, 0x3fb8aa3b, v41
	v_exp_f32_e32 v41, v41
	s_nop 0
	v_sub_f32_e32 v63, 1.0, v41
	v_cndmask_b32_e32 v63, v150, v63, vcc
	s_branch .LBB0_855
